# v65 + attention unmasked loop: running packed row-sum accumulators across iterations (16 fewer VALU per tile; rule 28 fewer-VALU lever)
# baseline (speedup 1.0000x reference)
; #define A_LOAD(t) do { _Pragma("unroll") for (int j_ = 0; j_ < 2; ++j_) { kreg[j_] = *(const u32x4*)(kg + (size_t)(64 * (t) + 32 * j_) * NIN); vreg[j_] = *(const u32x4*)(kg + 512 + (size_t)(64 * (t) + 32 * j_) * NIN); } } while (0)
; #define A_STORE(kbi, vbi) do { _Pragma("unroll") for (int j_ = 0; j_ < 2; ++j_) { *(LAS u32x4*)(lds + A_K0 + (kbi) * KBUF + (skey + 32 * j_) * KSTR + sch * 16) = kreg[j_]; *(LAS u32x4*)(lds + A_V0 + (vbi) * VBUF + (skey + 32 * j_) * VSTR + sch * 16) = vreg[j_]; } } while (0)
; __device__ __forceinline__ void attn_phase(LAS unsigned char* lds, const AttnArgs& a, int tid_in) {
;     ...
;         int t = 1, vp = 0, vn = 2;
;         for (; t < NTM; ++t) {
;             A_PIPE(false, t, vp);
;             A_STORE((t + 1) & 1, vn);
;             if (t + 2 < NT) A_LOAD(t + 2);
;             __syncthreads();
;             vp = (vp == 2) ? 0 : vp + 1; vn = (vn == 2) ? 0 : vn + 1;
;         }
.LBB0_578:
	v_cvt_pk_bf16_f32 v179, v14, v15
	s_cmp_lt_i32 s35, 2
	s_mov_b32 s34, 2
	s_waitcnt lgkmcnt(0)
	s_barrier
	s_cbranch_scc1 .LBB0_583
	v_mov_b32_e32 v64, 0
	s_mov_b32 s6, 0
	s_mov_b32 s4, 1
	s_movk_i32 s5, 0xe0
	v_mov_b32_e32 v65, v64
	v_mov_b32_e32 v66, v64
	v_mov_b32_e32 v67, v64
	v_mov_b32_e32 v68, v64
	v_mov_b32_e32 v69, v64
	v_mov_b32_e32 v70, v64
	v_mov_b32_e32 v71, v64
	v_mov_b32_e32 v72, v64
	v_mov_b32_e32 v73, v64
	v_mov_b32_e32 v74, v64
	v_mov_b32_e32 v75, v64
	v_mov_b32_e32 v76, v64
	v_mov_b32_e32 v77, v64
	v_mov_b32_e32 v78, v64
	v_mov_b32_e32 v79, v64
	v_mov_b32_e32 v80, v64
	v_mov_b32_e32 v81, v64
	v_mov_b32_e32 v82, v64
	v_mov_b32_e32 v83, v64
	v_mov_b32_e32 v84, v64
	v_mov_b32_e32 v85, v64
	v_mov_b32_e32 v86, v64
	v_mov_b32_e32 v87, v64
	v_mov_b32_e32 v88, v64
	v_mov_b32_e32 v89, v64
	v_mov_b32_e32 v90, v64
	v_mov_b32_e32 v91, v64
	v_mov_b32_e32 v92, v64
	v_mov_b32_e32 v93, v64
	v_mov_b32_e32 v94, v64
	v_mov_b32_e32 v95, v64
	v_mov_b32_e32 v48, v64
	v_mov_b32_e32 v49, v64
	v_mov_b32_e32 v50, v64
	v_mov_b32_e32 v51, v64
	v_mov_b32_e32 v52, v64
	v_mov_b32_e32 v53, v64
	v_mov_b32_e32 v54, v64
	v_mov_b32_e32 v55, v64
	v_mov_b32_e32 v56, v64
	v_mov_b32_e32 v57, v64
	v_mov_b32_e32 v58, v64
	v_mov_b32_e32 v59, v64
	v_mov_b32_e32 v60, v64
	v_mov_b32_e32 v61, v64
	v_mov_b32_e32 v62, v64
	v_mov_b32_e32 v63, v64
	v_mov_b32_e32 v32, v64
	v_mov_b32_e32 v33, v64
	v_mov_b32_e32 v34, v64
	v_mov_b32_e32 v35, v64
	v_mov_b32_e32 v36, v64
	v_mov_b32_e32 v37, v64
	v_mov_b32_e32 v38, v64
	v_mov_b32_e32 v39, v64
	v_mov_b32_e32 v40, v64
	v_mov_b32_e32 v41, v64
	v_mov_b32_e32 v42, v64
	v_mov_b32_e32 v43, v64
	v_mov_b32_e32 v44, v64
	v_mov_b32_e32 v45, v64
	v_mov_b32_e32 v46, v64
	v_mov_b32_e32 v47, v64
	v_mov_b32_e32 v18, 0
	v_mov_b32_e32 v19, 0
	v_mov_b32_e32 v14, 0
	v_mov_b32_e32 v15, 0
	s_branch .LBB0_581
.LBB0_581:
	s_setprio 1
	s_bitcmp1_b32 s4, 0
	s_cselect_b32 s30, 0x4400, 0
	v_add_u32_e32 v0, s30, v224
	ds_read_b128 v[2:5], v0
	ds_read_b128 v[6:9], v0 offset:32
	s_mul_i32 s30, s6, 0x5000
	s_waitcnt lgkmcnt(1)
	v_mfma_f32_32x32x16_bf16 v[128:143], v[2:5], v[144:147], v[96:111]
	ds_read_b128 v[2:5], v0 offset:8704
	ds_read_b128 v[10:13], v0 offset:8736
	s_waitcnt lgkmcnt(1)
	v_mfma_f32_32x32x16_bf16 v[112:127], v[2:5], v[144:147], v[96:111]
	v_mfma_f32_32x32x16_bf16 v[128:143], v[6:9], v[148:151], v[128:143]
	ds_read_b128 v[2:5], v0 offset:64
	ds_read_b128 v[6:9], v0 offset:96
	s_waitcnt lgkmcnt(2)
	v_mfma_f32_32x32x16_bf16 v[112:127], v[10:13], v[148:151], v[112:127]
	s_waitcnt lgkmcnt(1)
	v_mfma_f32_32x32x16_bf16 v[128:143], v[2:5], v[152:155], v[128:143]
	ds_read_b128 v[2:5], v0 offset:8768
	ds_read_b128 v[10:13], v0 offset:8800
	v_add_u32_e32 v0, s30, v225
	s_waitcnt lgkmcnt(1)
	v_mfma_f32_32x32x16_bf16 v[112:127], v[2:5], v[152:155], v[112:127]
	v_mfma_f32_32x32x16_bf16 v[128:143], v[6:9], v[156:159], v[128:143]
	ds_read_b64_tr_b16 v[2:3], v0 offset:34816
	ds_read_b64_tr_b16 v[6:7], v0 offset:34880
	ds_read_b64_tr_b16 v[236:237], v0 offset:34944
	ds_read_b64_tr_b16 v[240:241], v0 offset:35008
	ds_read_b64_tr_b16 v[4:5], v0 offset:37376
	ds_read_b64_tr_b16 v[8:9], v0 offset:37440
	ds_read_b64_tr_b16 v[238:239], v0 offset:37504
	ds_read_b64_tr_b16 v[242:243], v0 offset:37568
	s_waitcnt lgkmcnt(8)
	v_mfma_f32_32x32x16_bf16 v[112:127], v[10:13], v[156:159], v[112:127]
	s_waitcnt lgkmcnt(3)
	v_mfma_f32_32x32x16_bf16 v[64:79], v[188:191], v[2:5], v[64:79]
	ds_read_b64_tr_b16 v[2:3], v0 offset:39936
	ds_read_b64_tr_b16 v[4:5], v0 offset:42496
	v_exp_f32_e32 v128, v128
	v_exp_f32_e32 v129, v129
	v_exp_f32_e32 v130, v130
	v_pk_add_f32 v[18:19], v[18:19], v[128:129]
	s_waitcnt lgkmcnt(4)
	v_mfma_f32_32x32x16_bf16 v[80:95], v[188:191], v[6:9], v[80:95]
	ds_read_b64_tr_b16 v[6:7], v0 offset:40000
	ds_read_b64_tr_b16 v[8:9], v0 offset:42560
	v_exp_f32_e32 v131, v131
	v_exp_f32_e32 v132, v132
	v_exp_f32_e32 v133, v133
	v_pk_add_f32 v[18:19], v[18:19], v[130:131]
	s_waitcnt lgkmcnt(5)
	v_mfma_f32_32x32x16_bf16 v[48:63], v[188:191], v[236:239], v[48:63]
	ds_read_b64_tr_b16 v[10:11], v0 offset:40064
	ds_read_b64_tr_b16 v[12:13], v0 offset:42624
	v_exp_f32_e32 v134, v134
	v_exp_f32_e32 v135, v135
	v_exp_f32_e32 v136, v136
	v_pk_add_f32 v[18:19], v[18:19], v[132:133]
	s_waitcnt lgkmcnt(6)
	v_mfma_f32_32x32x16_bf16 v[32:47], v[188:191], v[240:243], v[32:47]
	ds_read_b64_tr_b16 v[28:29], v0 offset:40128
	ds_read_b64_tr_b16 v[30:31], v0 offset:42688
	v_exp_f32_e32 v137, v137
	v_exp_f32_e32 v138, v138
	v_exp_f32_e32 v139, v139
	v_cvt_pk_bf16_f32 v188, v128, v129
	s_waitcnt lgkmcnt(6)
; #define A_LOAD(t) do { _Pragma("unroll") for (int j_ = 0; j_ < 2; ++j_) { kreg[j_] = *(const u32x4*)(kg + (size_t)(64 * (t) + 32 * j_) * NIN); vreg[j_] = *(const u32x4*)(kg + 512 + (size_t)(64 * (t) + 32 * j_) * NIN); } } while (0)
; #define A_STORE(kbi, vbi) do { _Pragma("unroll") for (int j_ = 0; j_ < 2; ++j_) { *(LAS u32x4*)(lds + A_K0 + (kbi) * KBUF + (skey + 32 * j_) * KSTR + sch * 16) = kreg[j_]; *(LAS u32x4*)(lds + A_V0 + (vbi) * VBUF + (skey + 32 * j_) * VSTR + sch * 16) = vreg[j_]; } } while (0)
; __device__ __forceinline__ void attn_phase(LAS unsigned char* lds, const AttnArgs& a, int tid_in) {
;     ...
;         for (; t < NTM; ++t) {
;             A_PIPE(false, t, vp);
;             A_STORE((t + 1) & 1, vn);
;             if (t + 2 < NT) A_LOAD(t + 2);
;             __syncthreads();
;             vp = (vp == 2) ? 0 : vp + 1; vn = (vn == 2) ? 0 : vn + 1;
;         }
	v_mfma_f32_32x32x16_bf16 v[64:79], v[184:187], v[2:5], v[64:79]
	ds_read_b64_tr_b16 v[2:3], v0 offset:45056
	ds_read_b64_tr_b16 v[4:5], v0 offset:47616
	v_exp_f32_e32 v140, v140
	v_exp_f32_e32 v141, v141
	v_exp_f32_e32 v142, v142
	v_cvt_pk_bf16_f32 v189, v130, v131
	s_waitcnt lgkmcnt(6)
	v_mfma_f32_32x32x16_bf16 v[80:95], v[184:187], v[6:9], v[80:95]
	ds_read_b64_tr_b16 v[6:7], v0 offset:45120
	ds_read_b64_tr_b16 v[8:9], v0 offset:47680
	v_exp_f32_e32 v143, v143
	v_exp_f32_e32 v112, v112
	v_exp_f32_e32 v113, v113
	v_cvt_pk_bf16_f32 v190, v132, v133
	s_waitcnt lgkmcnt(6)
	v_mfma_f32_32x32x16_bf16 v[48:63], v[184:187], v[10:13], v[48:63]
	ds_read_b64_tr_b16 v[10:11], v0 offset:45184
	ds_read_b64_tr_b16 v[12:13], v0 offset:47744
	v_exp_f32_e32 v114, v114
	v_exp_f32_e32 v115, v115
	v_exp_f32_e32 v116, v116
	v_cvt_pk_bf16_f32 v191, v134, v135
	s_waitcnt lgkmcnt(6)
	v_mfma_f32_32x32x16_bf16 v[32:47], v[184:187], v[28:31], v[32:47]
	ds_read_b64_tr_b16 v[28:29], v0 offset:45248
	ds_read_b64_tr_b16 v[30:31], v0 offset:47808
	s_andn2_b32 s30, 1, s4
	s_mulk_i32 s30, 0x4400
	s_mul_i32 s31, s34, 0x5000
	v_add3_u32 v21, v223, s30, v228
	v_add3_u32 v22, v223, s31, v229
	v_exp_f32_e32 v117, v117
	v_exp_f32_e32 v118, v118
	v_exp_f32_e32 v119, v119
	v_cvt_pk_bf16_f32 v184, v136, v137
	s_waitcnt lgkmcnt(6)
	v_mfma_f32_32x32x16_bf16 v[64:79], v[180:183], v[2:5], v[64:79]
	ds_read_b64_tr_b16 v[2:3], v0 offset:50176
	ds_read_b64_tr_b16 v[4:5], v0 offset:52736
	s_waitcnt vmcnt(3)
	ds_write_b128 v21, v[160:163]
	v_exp_f32_e32 v120, v120
	v_exp_f32_e32 v121, v121
	v_exp_f32_e32 v122, v122
	v_cvt_pk_bf16_f32 v185, v138, v139
	s_waitcnt lgkmcnt(7)
	v_mfma_f32_32x32x16_bf16 v[80:95], v[180:183], v[6:9], v[80:95]
	ds_read_b64_tr_b16 v[6:7], v0 offset:50240
	ds_read_b64_tr_b16 v[8:9], v0 offset:52800
	s_waitcnt vmcnt(2)
	ds_write_b128 v22, v[164:167] offset:34816
	v_exp_f32_e32 v123, v123
	v_exp_f32_e32 v124, v124
	v_exp_f32_e32 v125, v125
	v_cvt_pk_bf16_f32 v186, v140, v141
	s_waitcnt lgkmcnt(8)
	v_mfma_f32_32x32x16_bf16 v[48:63], v[180:183], v[10:13], v[48:63]
	ds_read_b64_tr_b16 v[10:11], v0 offset:50304
	ds_read_b64_tr_b16 v[12:13], v0 offset:52864
	s_waitcnt vmcnt(1)
	ds_write_b128 v21, v[168:171] offset:8704
	v_exp_f32_e32 v126, v126
	v_exp_f32_e32 v127, v127
	v_cvt_pk_bf16_f32 v187, v142, v143
	v_pk_add_f32 v[18:19], v[18:19], v[134:135]
	v_pk_add_f32 v[18:19], v[18:19], v[136:137]
	s_waitcnt lgkmcnt(9)
	v_mfma_f32_32x32x16_bf16 v[32:47], v[180:183], v[28:31], v[32:47]
	ds_read_b64_tr_b16 v[28:29], v0 offset:50368
	ds_read_b64_tr_b16 v[30:31], v0 offset:52928
	s_waitcnt vmcnt(0)
	ds_write_b128 v22, v[172:175] offset:45056
	v_cvt_pk_bf16_f32 v180, v112, v113
	v_cvt_pk_bf16_f32 v181, v114, v115
	v_cvt_pk_bf16_f32 v182, v116, v117
	v_cvt_pk_bf16_f32 v183, v118, v119
	v_pk_add_f32 v[18:19], v[18:19], v[138:139]
	v_pk_add_f32 v[18:19], v[18:19], v[140:141]
	v_pk_add_f32 v[18:19], v[18:19], v[142:143]
	s_waitcnt lgkmcnt(10)
	v_mfma_f32_32x32x16_bf16 v[64:79], v[176:179], v[2:5], v[64:79]
	v_pk_add_f32 v[14:15], v[14:15], v[112:113]
	v_pk_add_f32 v[14:15], v[14:15], v[114:115]
	v_pk_add_f32 v[14:15], v[14:15], v[116:117]
	v_pk_add_f32 v[14:15], v[14:15], v[118:119]
	v_pk_add_f32 v[14:15], v[14:15], v[120:121]
	v_pk_add_f32 v[14:15], v[14:15], v[122:123]
	v_pk_add_f32 v[14:15], v[14:15], v[124:125]
	s_waitcnt lgkmcnt(7)
	v_mfma_f32_32x32x16_bf16 v[80:95], v[176:179], v[6:9], v[80:95]
	v_pk_add_f32 v[14:15], v[14:15], v[126:127]
	s_add_i32 s30, s4, 2
	s_cmp_ge_i32 s30, s27
	s_cbranch_scc1 .Lattn_u_skipld
	s_sub_i32 s30, s5, 32
	v_mad_u64_u32 v[24:25], s[30:31], s30, v219, v[202:203]
	v_mad_u64_u32 v[26:27], s[30:31], s5, v219, v[202:203]
	global_load_dwordx4 v[160:163], v[24:25], off
	global_load_dwordx4 v[164:167], v[24:25], off offset:1024
	global_load_dwordx4 v[168:171], v[26:27], off
	global_load_dwordx4 v[172:175], v[26:27], off offset:1024
.Lattn_u_skipld:
	s_waitcnt lgkmcnt(4)
	v_mfma_f32_32x32x16_bf16 v[48:63], v[176:179], v[10:13], v[48:63]
	s_waitcnt lgkmcnt(1)
	v_mfma_f32_32x32x16_bf16 v[32:47], v[176:179], v[28:31], v[32:47]
	v_cvt_pk_bf16_f32 v176, v120, v121
	v_cvt_pk_bf16_f32 v177, v122, v123
	v_cvt_pk_bf16_f32 v178, v124, v125
	v_cvt_pk_bf16_f32 v179, v126, v127
	s_setprio 0
	s_add_i32 s30, s6, 1
	s_cmp_lg_u32 s6, 2
	s_cselect_b32 s6, s30, 0
	s_add_i32 s30, s34, 1
	s_cmp_lg_u32 s34, 2
	s_cselect_b32 s34, s30, 0
	s_add_i32 s4, s4, 1
	s_add_i32 s5, s5, 64
	s_cmp_eq_u32 s35, s4
	s_waitcnt lgkmcnt(0)
	s_barrier
	s_cbranch_scc0 .LBB0_581
	v_pk_add_f32 v[18:19], v[18:19], v[14:15]
	s_nop 0
	v_add_f32_e32 v17, v18, v19
	v_add_f32_e32 v211, v211, v17
	s_branch .LBB0_584
